# NA first-half bias select uses the -30000 constant register as its false value; the 16 per-slot presets per tile are dropped
# speedup vs baseline: 1.0158x; 1.0053x over previous
.LBB0_1705:
	s_add_i32 s90, s14, 2
	v_add_u32_e32 v0, s2, v231
	ds_read_b64_tr_b16 v[194:195], v0 offset:24576
	ds_read_b64_tr_b16 v[196:197], v0 offset:25088
	s_waitcnt lgkmcnt(9)
	v_mfma_f32_32x32x16_bf16 v[96:111], v[190:193], v[142:145], 0
	v_add_f32_e32 v2, v64, v65
	v_add_f32_e32 v2, v66, v2
	v_add_f32_e32 v2, v67, v2
	v_add_f32_e32 v2, v68, v2
	v_add_f32_e32 v2, v69, v2
	v_cvt_pk_bf16_f32 v158, v64, v65
	v_cvt_pk_bf16_f32 v159, v66, v67
	ds_read_b64_tr_b16 v[10:11], v0 offset:28672
	ds_read_b64_tr_b16 v[12:13], v0 offset:29184
	s_waitcnt lgkmcnt(10)
	v_mfma_f32_32x32x16_bf16 v[114:129], v[182:185], v[142:145], 0
	v_add_f32_e32 v2, v70, v2
	v_add_f32_e32 v2, v71, v2
	v_add_f32_e32 v2, v72, v2
	v_add_f32_e32 v6, v73, v2
	v_cvt_pk_bf16_f32 v160, v68, v69
	v_cvt_pk_bf16_f32 v161, v70, v71
	ds_read_b64_tr_b16 v[2:3], v0 offset:25600
	ds_read_b64_tr_b16 v[4:5], v0 offset:26112
	s_waitcnt lgkmcnt(11)
	v_mfma_f32_32x32x16_bf16 v[96:111], v[186:189], v[138:141], v[96:111]
	v_add_f32_e32 v6, v74, v6
	v_add_f32_e32 v6, v75, v6
	v_add_f32_e32 v6, v76, v6
	v_add_f32_e32 v14, v77, v6
	v_cvt_pk_bf16_f32 v154, v72, v73
	v_cvt_pk_bf16_f32 v155, v74, v75
	ds_read_b64_tr_b16 v[6:7], v0 offset:29696
	ds_read_b64_tr_b16 v[8:9], v0 offset:30208
	s_waitcnt lgkmcnt(12)
	v_mfma_f32_32x32x16_bf16 v[114:129], v[178:181], v[138:141], v[114:129]
	v_add_f32_e32 v14, v78, v14
	v_add_f32_e32 v14, v79, v14
	v_add_f32_e32 v14, v80, v14
	v_add_f32_e32 v14, v81, v14
	v_cvt_pk_bf16_f32 v156, v76, v77
	v_cvt_pk_bf16_f32 v157, v78, v79
	ds_read_b64_tr_b16 v[178:179], v0 offset:26624
	ds_read_b64_tr_b16 v[180:181], v0 offset:27136
	s_waitcnt lgkmcnt(13)
	v_mfma_f32_32x32x16_bf16 v[96:111], v[174:177], v[134:137], v[96:111]
	v_add_f32_e32 v14, v82, v14
	v_add_f32_e32 v14, v83, v14
	v_add_f32_e32 v14, v84, v14
	v_add_f32_e32 v14, v85, v14
	v_cvt_pk_bf16_f32 v150, v80, v81
	v_cvt_pk_bf16_f32 v151, v82, v83
	ds_read_b64_tr_b16 v[174:175], v0 offset:30720
	ds_read_b64_tr_b16 v[176:177], v0 offset:31232
	s_waitcnt lgkmcnt(14)
	v_mfma_f32_32x32x16_bf16 v[114:129], v[170:173], v[134:137], v[114:129]
	v_add_f32_e32 v14, v86, v14
	v_add_f32_e32 v14, v87, v14
	v_add_f32_e32 v14, v88, v14
	v_add_f32_e32 v14, v89, v14
	v_cvt_pk_bf16_f32 v152, v84, v85
	v_cvt_pk_bf16_f32 v153, v86, v87
	ds_read_b64_tr_b16 v[170:171], v0 offset:27648
	ds_read_b64_tr_b16 v[172:173], v0 offset:28160
	s_waitcnt lgkmcnt(14)
	v_mfma_f32_32x32x16_bf16 v[96:111], v[166:169], v[130:133], v[96:111]
	v_add_f32_e32 v14, v90, v14
	v_add_f32_e32 v14, v91, v14
	v_add_f32_e32 v14, v92, v14
	v_add_f32_e32 v14, v93, v14
	v_cvt_pk_bf16_f32 v146, v88, v89
	v_cvt_pk_bf16_f32 v147, v90, v91
	ds_read_b64_tr_b16 v[166:167], v0 offset:31744
	ds_read_b64_tr_b16 v[168:169], v0 offset:32256
	v_mfma_f32_32x32x16_bf16 v[114:129], v[162:165], v[130:133], v[114:129]
	v_add_f32_e32 v0, v94, v14
	v_add_f32_e32 v0, v95, v0
	v_add_f32_e32 v0, 0, v0
	v_cvt_pk_bf16_f32 v148, v92, v93
	v_cvt_pk_bf16_f32 v149, v94, v95
	s_add_i32 s7, s14, 5
	s_cmp_lt_i32 s7, s0
	s_cselect_b32 s2, s7, s12
	s_cmp_gt_i32 s7, s6
	s_cselect_b32 s9, s95, 0
	s_cselect_b32 s8, s13, 0
	s_lshl_b64 s[10:11], s[2:3], 18
	v_lshl_add_u64 v[14:15], v[214:215], 0, s[10:11]
	s_add_i32 s2, s15, s97
	v_lshl_add_u64 v[14:15], s[8:9], 1, v[14:15]
	s_mov_b32 s7, m0
	s_mov_b32 m0, s2
	s_nop 0
	global_load_lds_dwordx4 v[14:15], off
	s_mov_b32 m0, s7
	s_add_i32 s2, s14, 3
	s_cmp_ge_i32 s2, s0
	s_cselect_b64 s[34:35], -1, 0
	s_cmp_lt_i32 s2, s0
	s_cselect_b32 s2, s2, s12
	s_cmp_ge_i32 s90, s6
	s_cselect_b64 s[36:37], -1, 0
	s_cmp_lt_i32 s90, s6
	s_cselect_b32 s9, 0, s95
	s_cselect_b32 s8, 0, s13
	s_lshl_b64 s[10:11], s[2:3], 18
	v_lshl_add_u64 v[14:15], v[216:217], 0, s[10:11]
	s_add_i32 s2, s89, s92
	v_lshl_add_u64 v[14:15], s[8:9], 1, v[14:15]
	s_mov_b32 s7, m0
	s_mov_b32 m0, s2
	s_nop 0
	global_load_lds_dwordx4 v[14:15], off
	s_mov_b32 m0, s7
	s_cmp_gt_i32 s90, s6
	s_cselect_b64 s[8:9], -1, 0
	v_pk_add_f32 v[112:113], v[96:97], v[218:219] op_sel_hi:[1,0] neg_lo:[0,1] neg_hi:[0,1]
	v_pk_add_f32 v[96:97], v[114:115], v[218:219] op_sel_hi:[1,0] neg_lo:[0,1] neg_hi:[0,1]
	v_pk_add_f32 v[114:115], v[98:99], v[218:219] op_sel_hi:[1,0] neg_lo:[0,1] neg_hi:[0,1]
	v_pk_add_f32 v[98:99], v[116:117], v[218:219] op_sel_hi:[1,0] neg_lo:[0,1] neg_hi:[0,1]
	v_pk_add_f32 v[116:117], v[100:101], v[218:219] op_sel_hi:[1,0] neg_lo:[0,1] neg_hi:[0,1]
	v_pk_add_f32 v[100:101], v[118:119], v[218:219] op_sel_hi:[1,0] neg_lo:[0,1] neg_hi:[0,1]
	v_pk_add_f32 v[118:119], v[102:103], v[218:219] op_sel_hi:[1,0] neg_lo:[0,1] neg_hi:[0,1]
	v_pk_add_f32 v[102:103], v[120:121], v[218:219] op_sel_hi:[1,0] neg_lo:[0,1] neg_hi:[0,1]
	v_pk_add_f32 v[120:121], v[104:105], v[218:219] op_sel_hi:[1,0] neg_lo:[0,1] neg_hi:[0,1]
	v_pk_add_f32 v[104:105], v[122:123], v[218:219] op_sel_hi:[1,0] neg_lo:[0,1] neg_hi:[0,1]
	v_pk_add_f32 v[122:123], v[106:107], v[218:219] op_sel_hi:[1,0] neg_lo:[0,1] neg_hi:[0,1]
	v_pk_add_f32 v[106:107], v[124:125], v[218:219] op_sel_hi:[1,0] neg_lo:[0,1] neg_hi:[0,1]
	v_pk_add_f32 v[124:125], v[108:109], v[218:219] op_sel_hi:[1,0] neg_lo:[0,1] neg_hi:[0,1]
	v_pk_add_f32 v[108:109], v[126:127], v[218:219] op_sel_hi:[1,0] neg_lo:[0,1] neg_hi:[0,1]
	v_pk_add_f32 v[126:127], v[110:111], v[218:219] op_sel_hi:[1,0] neg_lo:[0,1] neg_hi:[0,1]
	v_pk_add_f32 v[110:111], v[128:129], v[218:219] op_sel_hi:[1,0] neg_lo:[0,1] neg_hi:[0,1]
	s_mov_b64 s[10:11], -1
	s_and_b64 vcc, exec, s[8:9]
	s_cbranch_vccnz .LBB0_1742
	s_add_i32 s2, s96, s14
	s_add_i32 s2, s2, 2
	s_cmp_lt_u32 s2, s93
	s_cselect_b64 s[10:11], -1, 0
	s_cmp_gt_u32 s2, s1
	s_cselect_b64 vcc, -1, 0
	s_or_b64 s[10:11], s[10:11], vcc
	s_and_b64 vcc, exec, s[10:11]
	s_cbranch_vccnz .LBB0_1740
	ds_read_b32 v14, v207 offset:128
	ds_read_b32 v235, v207
	ds_read_b32 v15, v207 offset:132
	ds_read_b32 v236, v207 offset:4
	ds_read_b32 v17, v207 offset:136
	ds_read_b32 v237, v207 offset:8
	ds_read_b32 v18, v207 offset:140
	ds_read_b32 v238, v207 offset:12
	ds_read_b32 v19, v207 offset:160
	ds_read_b32 v239, v207 offset:32
	ds_read_b32 v20, v207 offset:164
	ds_read_b32 v240, v207 offset:36
	ds_read_b32 v21, v207 offset:168
	ds_read_b32 v241, v207 offset:40
	ds_read_b32 v22, v207 offset:172
	ds_read_b32 v242, v207 offset:44
	s_waitcnt lgkmcnt(8)
	v_add_f32_e32 v251, v112, v235
	v_cndmask_b32_e64 v64, v16, v251, s[40:41]
	v_add_f32_e32 v251, v113, v236
	v_cndmask_b32_e64 v65, v16, v251, s[44:45]
	v_add_f32_e32 v251, v114, v237
	v_cndmask_b32_e64 v66, v16, v251, s[48:49]
	v_add_f32_e32 v251, v115, v238
	v_cndmask_b32_e64 v67, v16, v251, s[52:53]
	ds_read_b32 v23, v207 offset:192
	ds_read_b32 v243, v207 offset:64
	ds_read_b32 v24, v207 offset:196
	ds_read_b32 v244, v207 offset:68
	ds_read_b32 v25, v207 offset:200
	ds_read_b32 v245, v207 offset:72
	ds_read_b32 v26, v207 offset:204
	ds_read_b32 v246, v207 offset:76
	s_waitcnt lgkmcnt(8)
	v_add_f32_e32 v251, v116, v239
	v_cndmask_b32_e64 v68, v16, v251, s[56:57]
	v_add_f32_e32 v251, v117, v240
	v_cndmask_b32_e64 v69, v16, v251, s[60:61]
	v_add_f32_e32 v251, v118, v241
	v_cndmask_b32_e64 v70, v16, v251, s[64:65]
	v_add_f32_e32 v251, v119, v242
	v_cndmask_b32_e64 v71, v16, v251, s[68:69]
	ds_read_b32 v27, v207 offset:224
	ds_read_b32 v247, v207 offset:96
	ds_read_b32 v28, v207 offset:228
	ds_read_b32 v248, v207 offset:100
	ds_read_b32 v29, v207 offset:232
	ds_read_b32 v249, v207 offset:104
	ds_read_b32 v30, v207 offset:236
	ds_read_b32 v250, v207 offset:108
	s_waitcnt lgkmcnt(8)
	v_add_f32_e32 v251, v120, v243
	v_cndmask_b32_e64 v72, v16, v251, s[16:17]
	v_add_f32_e32 v251, v121, v244
	v_cndmask_b32_e64 v73, v16, v251, s[18:19]
	v_add_f32_e32 v251, v122, v245
	v_cndmask_b32_e64 v74, v16, v251, s[20:21]
	v_add_f32_e32 v251, v123, v246
	v_cndmask_b32_e64 v75, v16, v251, s[22:23]
	s_waitcnt lgkmcnt(14)
	v_add_f32_e32 v14, v96, v14
	v_cndmask_b32_e64 v80, v16, v14, s[42:43]
	v_add_f32_e32 v14, v97, v15
	v_cndmask_b32_e64 v81, v16, v14, s[46:47]
	s_waitcnt lgkmcnt(13)
	v_add_f32_e32 v14, v98, v17
	v_cndmask_b32_e64 v82, v16, v14, s[50:51]
	s_waitcnt lgkmcnt(12)
	v_add_f32_e32 v14, v99, v18
	v_cndmask_b32_e64 v83, v16, v14, s[54:55]
	s_waitcnt lgkmcnt(11)
	v_add_f32_e32 v14, v100, v19
	v_cndmask_b32_e64 v84, v16, v14, s[58:59]
	s_waitcnt lgkmcnt(10)
	v_add_f32_e32 v14, v101, v20
	v_cndmask_b32_e64 v85, v16, v14, s[62:63]
	s_waitcnt lgkmcnt(9)
	v_add_f32_e32 v14, v102, v21
	v_cndmask_b32_e64 v86, v16, v14, s[66:67]
	s_waitcnt lgkmcnt(8)
	v_add_f32_e32 v14, v103, v22
	v_cndmask_b32_e64 v87, v16, v14, s[70:71]
	s_waitcnt lgkmcnt(7)
	v_add_f32_e32 v14, v104, v23
	v_cndmask_b32_e64 v88, v16, v14, s[72:73]
	s_waitcnt lgkmcnt(6)
	v_add_f32_e32 v14, v105, v24
	v_cndmask_b32_e64 v89, v16, v14, s[74:75]
	s_waitcnt lgkmcnt(5)
	v_add_f32_e32 v14, v106, v25
	v_cndmask_b32_e64 v90, v16, v14, s[76:77]
	s_waitcnt lgkmcnt(4)
	v_add_f32_e32 v14, v107, v26
	v_cndmask_b32_e64 v91, v16, v14, s[78:79]
	s_waitcnt lgkmcnt(3)
	v_add_f32_e32 v14, v108, v27
	v_cndmask_b32_e64 v92, v16, v14, s[80:81]
	s_waitcnt lgkmcnt(2)
	v_add_f32_e32 v14, v109, v28
	v_cndmask_b32_e64 v93, v16, v14, s[82:83]
	s_waitcnt lgkmcnt(1)
	v_add_f32_e32 v14, v110, v29
	v_cndmask_b32_e64 v94, v16, v14, s[84:85]
	s_waitcnt lgkmcnt(0)
	v_add_f32_e32 v14, v111, v30
	v_cndmask_b32_e64 v95, v16, v14, s[86:87]
	v_add_f32_e32 v251, v124, v247
	v_cndmask_b32_e64 v76, v16, v251, s[24:25]
	v_add_f32_e32 v251, v125, v248
	v_cndmask_b32_e64 v77, v16, v251, s[26:27]
	v_add_f32_e32 v251, v126, v249
	v_cndmask_b32_e64 v78, v16, v251, s[28:29]
	v_add_f32_e32 v251, v127, v250
	v_cndmask_b32_e64 v79, v16, v251, s[30:31]
	s_branch .LBB0_1741

.LBB0_1753:
	s_add_i32 s2, s96, s14
	s_add_i32 s2, s2, 3
	s_cmp_lt_u32 s2, s93
	s_cselect_b64 s[8:9], -1, 0
	s_cmp_gt_u32 s2, s1
	s_cselect_b64 s[10:11], -1, 0
	s_or_b64 s[8:9], s[8:9], s[10:11]
	s_and_b64 vcc, exec, s[8:9]
	s_cbranch_vccnz .LBB0_1788
	ds_read_b32 v17, v207 offset:252
	ds_read_b32 v235, v207 offset:124
	ds_read_b32 v18, v207 offset:256
	ds_read_b32 v236, v207 offset:128
	ds_read_b32 v19, v207 offset:260
	ds_read_b32 v237, v207 offset:132
	ds_read_b32 v20, v207 offset:264
	ds_read_b32 v238, v207 offset:136
	ds_read_b32 v21, v207 offset:284
	ds_read_b32 v239, v207 offset:156
	ds_read_b32 v22, v207 offset:288
	ds_read_b32 v240, v207 offset:160
	ds_read_b32 v23, v207 offset:292
	ds_read_b32 v241, v207 offset:164
	ds_read_b32 v24, v207 offset:296
	ds_read_b32 v242, v207 offset:168
	s_waitcnt lgkmcnt(8)
	v_add_f32_e32 v251, v112, v235
	v_cndmask_b32_e64 v64, v16, v251, s[40:41]
	v_add_f32_e32 v251, v113, v236
	v_cndmask_b32_e64 v65, v16, v251, s[44:45]
	v_add_f32_e32 v251, v114, v237
	v_cndmask_b32_e64 v66, v16, v251, s[48:49]
	v_add_f32_e32 v251, v115, v238
	v_cndmask_b32_e64 v67, v16, v251, s[52:53]
	ds_read_b32 v25, v207 offset:316
	ds_read_b32 v243, v207 offset:188
	ds_read_b32 v26, v207 offset:320
	ds_read_b32 v244, v207 offset:192
	ds_read_b32 v27, v207 offset:324
	ds_read_b32 v245, v207 offset:196
	ds_read_b32 v28, v207 offset:328
	ds_read_b32 v246, v207 offset:200
	s_waitcnt lgkmcnt(8)
	v_add_f32_e32 v251, v116, v239
	v_cndmask_b32_e64 v68, v16, v251, s[56:57]
	v_add_f32_e32 v251, v117, v240
	v_cndmask_b32_e64 v69, v16, v251, s[60:61]
	v_add_f32_e32 v251, v118, v241
	v_cndmask_b32_e64 v70, v16, v251, s[64:65]
	v_add_f32_e32 v251, v119, v242
	v_cndmask_b32_e64 v71, v16, v251, s[68:69]
	ds_read_b32 v29, v207 offset:348
	ds_read_b32 v247, v207 offset:220
	ds_read_b32 v30, v207 offset:352
	ds_read_b32 v248, v207 offset:224
	ds_read_b32 v31, v207 offset:356
	ds_read_b32 v249, v207 offset:228
	ds_read_b32 v95, v207 offset:360
	ds_read_b32 v250, v207 offset:232
	s_waitcnt lgkmcnt(8)
	v_add_f32_e32 v251, v120, v243
	v_cndmask_b32_e64 v72, v16, v251, s[16:17]
	v_add_f32_e32 v251, v121, v244
	v_cndmask_b32_e64 v73, v16, v251, s[18:19]
	v_add_f32_e32 v251, v122, v245
	v_cndmask_b32_e64 v74, v16, v251, s[20:21]
	v_add_f32_e32 v251, v123, v246
	v_cndmask_b32_e64 v75, v16, v251, s[22:23]
	s_waitcnt lgkmcnt(14)
	v_add_f32_e32 v17, v96, v17
	v_cndmask_b32_e64 v80, v16, v17, s[42:43]
	v_add_f32_e32 v17, v97, v18
	v_cndmask_b32_e64 v81, v16, v17, s[46:47]
	s_waitcnt lgkmcnt(13)
	v_add_f32_e32 v17, v98, v19
	v_cndmask_b32_e64 v82, v16, v17, s[50:51]
	s_waitcnt lgkmcnt(12)
	v_add_f32_e32 v17, v99, v20
	v_cndmask_b32_e64 v83, v16, v17, s[54:55]
	s_waitcnt lgkmcnt(11)
	v_add_f32_e32 v17, v100, v21
	v_cndmask_b32_e64 v84, v16, v17, s[58:59]
	s_waitcnt lgkmcnt(10)
	v_add_f32_e32 v17, v101, v22
	v_cndmask_b32_e64 v85, v16, v17, s[62:63]
	s_waitcnt lgkmcnt(9)
	v_add_f32_e32 v17, v102, v23
	v_cndmask_b32_e64 v86, v16, v17, s[66:67]
	s_waitcnt lgkmcnt(8)
	v_add_f32_e32 v17, v103, v24
	v_cndmask_b32_e64 v87, v16, v17, s[70:71]
	s_waitcnt lgkmcnt(7)
	v_add_f32_e32 v17, v104, v25
	v_cndmask_b32_e64 v88, v16, v17, s[72:73]
	s_waitcnt lgkmcnt(6)
	v_add_f32_e32 v17, v105, v26
	v_cndmask_b32_e64 v89, v16, v17, s[74:75]
	s_waitcnt lgkmcnt(5)
	v_add_f32_e32 v17, v106, v27
	v_cndmask_b32_e64 v90, v16, v17, s[76:77]
	s_waitcnt lgkmcnt(4)
	v_add_f32_e32 v17, v107, v28
	v_cndmask_b32_e64 v91, v16, v17, s[78:79]
	s_waitcnt lgkmcnt(3)
	v_add_f32_e32 v17, v108, v29
	v_cndmask_b32_e64 v92, v16, v17, s[80:81]
	s_waitcnt lgkmcnt(2)
	v_add_f32_e32 v17, v109, v30
	v_cndmask_b32_e64 v93, v16, v17, s[82:83]
	s_waitcnt lgkmcnt(1)
	v_add_f32_e32 v17, v110, v31
	v_cndmask_b32_e64 v94, v16, v17, s[84:85]
	s_waitcnt lgkmcnt(0)
	v_add_f32_e32 v17, v111, v95
	v_cndmask_b32_e64 v95, v16, v17, s[86:87]
	v_add_f32_e32 v251, v124, v247
	v_cndmask_b32_e64 v76, v16, v251, s[24:25]
	v_add_f32_e32 v251, v125, v248
	v_cndmask_b32_e64 v77, v16, v251, s[26:27]
	v_add_f32_e32 v251, v126, v249
	v_cndmask_b32_e64 v78, v16, v251, s[28:29]
	v_add_f32_e32 v251, v127, v250
	v_cndmask_b32_e64 v79, v16, v251, s[30:31]
	s_branch .LBB0_1789
